# mirror of the previous version: the static s_setprio 1 on waves 0-3 instead of 4-7
# speedup vs baseline: 1.0101x; 1.0072x over previous
.Lhf_done:
	s_barrier
	s_cmp_lt_u32 s86, 0x100
	s_cbranch_scc0 .Lprio_a
	s_setprio 1

.LBB0_514:
	s_or_b64 exec, exec, s[4:5]
	s_mov_b64 s[4:5], s[66:67]
	v_mov_b32_e32 v0, v1
	s_waitcnt lgkmcnt(0)
	s_barrier
	s_cmp_lt_u32 s86, 0x100
	s_cbranch_scc0 .Lprio_0
	s_setprio 1

.LBB0_1310:
	s_or_b64 exec, exec, s[6:7]
	s_mov_b64 s[6:7], s[66:67]
	v_mov_b32_e32 v0, v1
	s_waitcnt lgkmcnt(0)
	s_barrier
	s_cmp_lt_u32 s86, 0x100
	s_cbranch_scc0 .Lprio_1
	s_setprio 1
